# attention online softmax: running max is only raised when the tile max exceeds it by more than 8 (log2 units), so the O rescale multiply is skipped for most tiles; exact same normalised result
# speedup vs baseline: 1.0240x; 1.0057x over previous
; #define MFMA16(a, b, c) __builtin_amdgcn_mfma_f32_16x16x32_bf16((a), (b), (c), 0, 0, 0)
; DI void u_attn2(Frame& F, int h, int qb, int sp, int ntile) {
;     ...
;             {
;                 bf16x8 kfr[2][4];
; #pragma unroll
;                 for (int kb = 0; kb < 4; ++kb) kfr[0][kb] = ldfrag(Ks, 200, kb * 16, 0, lane);
; #pragma unroll
;                 for (int ks = 0; ks < 6; ++ks) {
;                     if (ks < 5) {
; #pragma unroll
;                         for (int kb = 0; kb < 4; ++kb) kfr[(ks + 1) & 1][kb] = ldfrag(Ks, 200, kb * 16, (ks + 1) * 32, lane); }
; #pragma unroll
;                     for (int kb = 0; kb < 4; ++kb)
; #pragma unroll
;                         for (int qq = 0; qq < 2; ++qq) s[kb][qq] = MFMA16(kfr[ks & 1][kb], qf[qq][ks], s[kb][qq]);
;                 }
;             }
.Latt_A_qk:
	v_cmp_lt_i32_e32 vcc, s46, v179
	s_cbranch_vccz .LBB0_2236
	v_add_u32_e32 v18, s46, v181
	v_cmp_le_i32_e32 vcc, v18, v180
	s_cbranch_vccz .LBB0_2236
	ds_read_b128 v[138:141], v113
	ds_read_b128 v[142:145], v113 offset:6656
	ds_read_b128 v[146:149], v113 offset:13312
	ds_read_b128 v[150:153], v113 offset:19968
	ds_read_b128 v[154:157], v113 offset:64
	ds_read_b128 v[192:195], v113 offset:6720
	ds_read_b128 v[210:213], v113 offset:13376
	ds_read_b128 v[214:217], v113 offset:20032
	s_waitcnt lgkmcnt(7)
	v_mfma_f32_16x16x32_bf16 v[218:221], v[138:141], v[2:5], 0
	ds_read_b128 v[244:247], v113 offset:128
	ds_read_b128 v[248:251], v113 offset:6784
	ds_read_b128 v[198:201], v113 offset:13440
	ds_read_b128 v[230:233], v113 offset:20096
	v_mov_b32_e32 v234, 0x42800000
	v_mfma_f32_16x16x32_bf16 v[138:141], v[138:141], v[30:33], 0
	s_waitcnt lgkmcnt(10)
	v_mfma_f32_16x16x32_bf16 v[222:225], v[142:145], v[2:5], 0
	v_mfma_f32_16x16x32_bf16 v[142:145], v[142:145], v[30:33], 0
	s_waitcnt lgkmcnt(9)
	v_mfma_f32_16x16x32_bf16 v[226:229], v[146:149], v[2:5], 0
	s_waitcnt lgkmcnt(7)
	v_mfma_f32_16x16x32_bf16 v[218:221], v[154:157], v[6:9], v[218:221]
	v_mfma_f32_16x16x32_bf16 v[146:149], v[146:149], v[30:33], 0
	v_mfma_f32_16x16x32_bf16 v[240:243], v[150:153], v[2:5], 0
	v_mfma_f32_16x16x32_bf16 v[150:153], v[150:153], v[30:33], 0
	v_mfma_f32_16x16x32_bf16 v[138:141], v[154:157], v[34:37], v[138:141]
	s_waitcnt lgkmcnt(6)
	v_mfma_f32_16x16x32_bf16 v[154:157], v[192:195], v[6:9], v[222:225]
	v_mfma_f32_16x16x32_bf16 v[142:145], v[192:195], v[34:37], v[142:145]
	s_waitcnt lgkmcnt(5)
	v_mfma_f32_16x16x32_bf16 v[192:195], v[210:213], v[6:9], v[226:229]
	s_waitcnt lgkmcnt(3)
	v_mfma_f32_16x16x32_bf16 v[218:221], v[244:247], v[10:13], v[218:221]
	v_mfma_f32_16x16x32_bf16 v[146:149], v[210:213], v[34:37], v[146:149]
	v_mfma_f32_16x16x32_bf16 v[210:213], v[214:217], v[6:9], v[240:243]
	v_mfma_f32_16x16x32_bf16 v[150:153], v[214:217], v[34:37], v[150:153]
	ds_read_b128 v[214:217], v113 offset:192
	ds_read_b128 v[222:225], v113 offset:6848
	ds_read_b128 v[226:229], v113 offset:13504
	ds_read_b128 v[240:243], v113 offset:20160
	v_mfma_f32_16x16x32_bf16 v[138:141], v[244:247], v[38:41], v[138:141]
	s_waitcnt lgkmcnt(6)
	v_mfma_f32_16x16x32_bf16 v[154:157], v[248:251], v[10:13], v[154:157]
	v_mfma_f32_16x16x32_bf16 v[142:145], v[248:251], v[38:41], v[142:145]
	s_waitcnt lgkmcnt(5)
	v_mfma_f32_16x16x32_bf16 v[192:195], v[198:201], v[10:13], v[192:195]
	s_waitcnt lgkmcnt(3)
	v_mfma_f32_16x16x32_bf16 v[218:221], v[214:217], v[14:17], v[218:221]
	v_mfma_f32_16x16x32_bf16 v[146:149], v[198:201], v[38:41], v[146:149]
	v_mfma_f32_16x16x32_bf16 v[198:201], v[230:233], v[10:13], v[210:213]
	v_mfma_f32_16x16x32_bf16 v[150:153], v[230:233], v[38:41], v[150:153]
	s_nop 1
	ds_read_b128 v[210:213], v113 offset:256
	ds_read_b128 v[230:233], v113 offset:6912
	ds_read_b128 v[244:247], v113 offset:13568
	ds_read_b128 v[248:251], v113 offset:20224
	v_mfma_f32_16x16x32_bf16 v[138:141], v[214:217], v[42:45], v[138:141]
	s_waitcnt lgkmcnt(6)
	v_mfma_f32_16x16x32_bf16 v[154:157], v[222:225], v[14:17], v[154:157]
	v_mfma_f32_16x16x32_bf16 v[142:145], v[222:225], v[42:45], v[142:145]
	s_waitcnt lgkmcnt(5)
	v_mfma_f32_16x16x32_bf16 v[192:195], v[226:229], v[14:17], v[192:195]
	s_waitcnt lgkmcnt(3)
	v_mfma_f32_16x16x32_bf16 v[218:221], v[210:213], v[22:25], v[218:221]
	v_mfma_f32_16x16x32_bf16 v[198:201], v[240:243], v[14:17], v[198:201]
	v_mfma_f32_16x16x32_bf16 v[150:153], v[240:243], v[42:45], v[150:153]
	v_mfma_f32_16x16x32_bf16 v[138:141], v[210:213], v[46:49], v[138:141]
	s_waitcnt lgkmcnt(2)
	v_mfma_f32_16x16x32_bf16 v[154:157], v[230:233], v[22:25], v[154:157]
	v_mfma_f32_16x16x32_bf16 v[146:149], v[226:229], v[42:45], v[146:149]
	ds_read_b128 v[214:217], v113 offset:320
	ds_read_b128 v[222:225], v113 offset:6976
	ds_read_b128 v[226:229], v113 offset:13632
	ds_read_b128 v[240:243], v113 offset:20288
	v_mfma_f32_16x16x32_bf16 v[142:145], v[230:233], v[46:49], v[142:145]
	s_waitcnt lgkmcnt(5)
	v_mfma_f32_16x16x32_bf16 v[192:195], v[244:247], v[22:25], v[192:195]
	s_waitcnt lgkmcnt(3)
; DI float xr16_max(float x) { float a = x, b = x; XR_SWAP("v_permlane16_swap_b32", a, b); return fmaxf(a, b); }
; DI float xr32_max(float x) { float a = x, b = x; XR_SWAP("v_permlane32_swap_b32", a, b); return fmaxf(a, b); }
; DI float xr16_sum(float x) { float a = x, b = x; XR_SWAP("v_permlane16_swap_b32", a, b); return a + b; }
; DI float xr32_sum(float x) { float a = x, b = x; XR_SWAP("v_permlane32_swap_b32", a, b); return a + b; }
; #define MFMA16(a, b, c) __builtin_amdgcn_mfma_f32_16x16x32_bf16((a), (b), (c), 0, 0, 0)
; DI void u_attn2(Frame& F, int h, int qb, int sp, int ntile) {
;     ...
;                     for (int kb = 0; kb < 4; ++kb)
; #pragma unroll
;                         for (int qq = 0; qq < 2; ++qq) s[kb][qq] = MFMA16(kfr[ks & 1][kb], qf[qq][ks], s[kb][qq]);
;                 }
;             }
;             bf16x8 pf[2][2];
; #pragma unroll
;             for (int qq = 0; qq < 2; ++qq) {
;                 float mx = -1e30f;
; #pragma unroll
;                 for (int kb = 0; kb < 4; ++kb) mx = fmaxf(mx, fmaxf(fmaxf(s[kb][qq][0], s[kb][qq][1]), fmaxf(s[kb][qq][2], s[kb][qq][3])));
;                 mx = xr32_max(xr16_max(mx));
;                 const float mn = fmaxf(mrun[qq], mx), alpha = __builtin_amdgcn_exp2f(mrun[qq] - mn); mrun[qq] = mn;
;                 float ps = 0.f; float p[16];
; #pragma unroll
;                 for (int kb = 0; kb < 4; ++kb)
; #pragma unroll
;                     for (int r = 0; r < 4; ++r) { p[kb * 4 + r] = __builtin_amdgcn_exp2f(s[kb][qq][r] - mn); ps += p[kb * 4 + r]; }
;                 ps = xr32_sum(xr16_sum(ps));
;                 lrun[qq] = lrun[qq] * alpha + ps;
; if (__builtin_amdgcn_ballot_w64(alpha != 1.0f) != 0ull) {
; #pragma unroll
;                     for (int db = 0; db < 8; ++db) o[db][qq] = o[db][qq] * alpha; }
	v_mfma_f32_16x16x32_bf16 v[218:221], v[214:217], v[26:29], v[218:221]
	v_mfma_f32_16x16x32_bf16 v[198:201], v[248:251], v[22:25], v[198:201]
	v_mfma_f32_16x16x32_bf16 v[230:233], v[248:251], v[46:49], v[150:153]
	v_mfma_f32_16x16x32_bf16 v[150:153], v[214:217], v[50:53], v[138:141]
	s_waitcnt lgkmcnt(2)
	v_mfma_f32_16x16x32_bf16 v[214:217], v[222:225], v[26:29], v[154:157]
	v_mfma_f32_16x16x32_bf16 v[210:213], v[244:247], v[46:49], v[146:149]
	v_mfma_f32_16x16x32_bf16 v[146:149], v[222:225], v[50:53], v[142:145]
	s_waitcnt lgkmcnt(1)
	v_mfma_f32_16x16x32_bf16 v[222:225], v[226:229], v[26:29], v[192:195]
	s_waitcnt lgkmcnt(0)
	v_mfma_f32_16x16x32_bf16 v[154:157], v[240:243], v[26:29], v[198:201]
	v_mfma_f32_16x16x32_bf16 v[138:141], v[240:243], v[50:53], v[230:233]
	s_nop 1
	v_mfma_f32_16x16x32_bf16 v[142:145], v[226:229], v[50:53], v[210:213]
	s_nop 7
	s_nop 1
	v_max3_f32 v198, v218, v219, v220
	v_max3_f32 v210, v150, v151, v152
	v_max3_f32 v199, v221, v214, v215
	v_max3_f32 v211, v153, v146, v147
	v_max3_f32 v200, v216, v217, v222
	v_max3_f32 v212, v148, v149, v142
	v_max3_f32 v201, v223, v224, v225
	v_max3_f32 v213, v143, v144, v145
	v_max3_f32 v192, v154, v155, v156
	v_max3_f32 v193, v138, v139, v140
	v_max3_f32 v198, v198, v199, v157
	v_max3_f32 v210, v210, v211, v141
	v_max3_f32 v200, v200, v201, v192
	v_max3_f32 v212, v212, v213, v193
	v_max3_f32 v18, v198, v200, s1
	v_max3_f32 v20, v210, v212, s1
	v_mov_b32_e32 v198, v18
	v_mov_b32_e32 v210, v20
	s_nop 0
	v_permlane16_swap_b32 v18, v198
	v_permlane16_swap_b32 v20, v210
	s_nop 0
	v_max_f32_e32 v18, v18, v198
	v_max_f32_e32 v20, v20, v210
	v_mov_b32_e32 v198, v18
	v_mov_b32_e32 v210, v20
	s_nop 0
	v_permlane32_swap_b32 v18, v198
	v_permlane32_swap_b32 v20, v210
	s_nop 0
	v_max_f32_e32 v18, v18, v198
	v_max_f32_e32 v20, v20, v210
	v_add_f32_e32 v198, 0x41000000, v164
	v_add_f32_e32 v210, 0x41000000, v162
	v_cmp_gt_f32_e32 vcc, v18, v198
	v_cndmask_b32_e32 v21, v164, v18, vcc
	v_cmp_gt_f32_e32 vcc, v20, v210
	v_cndmask_b32_e32 v191, v162, v20, vcc
	v_sub_f32_e32 v18, v164, v21
	v_sub_f32_e32 v20, v162, v191
	v_exp_f32_e32 v18, v18
	v_exp_f32_e32 v20, v20
	v_sub_f32_e32 v218, v218, v21
	v_sub_f32_e32 v219, v219, v21
	v_sub_f32_e32 v220, v220, v21
	v_sub_f32_e32 v221, v221, v21
	v_sub_f32_e32 v214, v214, v21
	v_sub_f32_e32 v215, v215, v21
	v_sub_f32_e32 v216, v216, v21
	v_sub_f32_e32 v217, v217, v21
	v_sub_f32_e32 v222, v222, v21
	v_sub_f32_e32 v223, v223, v21
	v_sub_f32_e32 v224, v224, v21
	v_sub_f32_e32 v225, v225, v21
	v_sub_f32_e32 v154, v154, v21
	v_sub_f32_e32 v155, v155, v21
	v_sub_f32_e32 v156, v156, v21
	v_sub_f32_e32 v157, v157, v21
	v_sub_f32_e32 v150, v150, v191
	v_sub_f32_e32 v151, v151, v191
	v_sub_f32_e32 v152, v152, v191
	v_sub_f32_e32 v153, v153, v191
	v_sub_f32_e32 v146, v146, v191
	v_sub_f32_e32 v147, v147, v191
	v_sub_f32_e32 v148, v148, v191
	v_sub_f32_e32 v149, v149, v191
	v_sub_f32_e32 v142, v142, v191
	v_sub_f32_e32 v143, v143, v191
	v_sub_f32_e32 v144, v144, v191
	v_sub_f32_e32 v145, v145, v191
	v_sub_f32_e32 v138, v138, v191
	v_sub_f32_e32 v139, v139, v191
	v_sub_f32_e32 v140, v140, v191
	v_sub_f32_e32 v141, v141, v191
	v_cmp_neq_f32_e32 vcc, 1.0, v18
	s_cbranch_vccz .Latt_r0_A
	v_pk_mul_f32 v[136:137], v[136:137], v[18:19] op_sel_hi:[1,0]
	v_pk_mul_f32 v[134:135], v[134:135], v[18:19] op_sel_hi:[1,0]
	v_pk_mul_f32 v[108:109], v[108:109], v[18:19] op_sel_hi:[1,0]
	v_pk_mul_f32 v[106:107], v[106:107], v[18:19] op_sel_hi:[1,0]
	v_pk_mul_f32 v[100:101], v[100:101], v[18:19] op_sel_hi:[1,0]
	v_pk_mul_f32 v[98:99], v[98:99], v[18:19] op_sel_hi:[1,0]
	v_pk_mul_f32 v[92:93], v[92:93], v[18:19] op_sel_hi:[1,0]
	v_pk_mul_f32 v[90:91], v[90:91], v[18:19] op_sel_hi:[1,0]
	v_pk_mul_f32 v[84:85], v[84:85], v[18:19] op_sel_hi:[1,0]
	v_pk_mul_f32 v[82:83], v[82:83], v[18:19] op_sel_hi:[1,0]
	v_pk_mul_f32 v[72:73], v[72:73], v[18:19] op_sel_hi:[1,0]
	v_pk_mul_f32 v[70:71], v[70:71], v[18:19] op_sel_hi:[1,0]
	v_pk_mul_f32 v[68:69], v[68:69], v[18:19] op_sel_hi:[1,0]
	v_pk_mul_f32 v[66:67], v[66:67], v[18:19] op_sel_hi:[1,0]
	v_pk_mul_f32 v[56:57], v[56:57], v[18:19] op_sel_hi:[1,0]
	v_pk_mul_f32 v[54:55], v[54:55], v[18:19] op_sel_hi:[1,0]

; DI float xr16_max(float x) { float a = x, b = x; XR_SWAP("v_permlane16_swap_b32", a, b); return fmaxf(a, b); }
; DI float xr32_max(float x) { float a = x, b = x; XR_SWAP("v_permlane32_swap_b32", a, b); return fmaxf(a, b); }
; DI float xr16_sum(float x) { float a = x, b = x; XR_SWAP("v_permlane16_swap_b32", a, b); return a + b; }
; DI float xr32_sum(float x) { float a = x, b = x; XR_SWAP("v_permlane32_swap_b32", a, b); return a + b; }
; DI void u_attn2(Frame& F, int h, int qb, int sp, int ntile) {
;     ...
;                 float mx = -1e30f;
; #pragma unroll
;                 for (int kb = 0; kb < 4; ++kb) mx = fmaxf(mx, fmaxf(fmaxf(s[kb][qq][0], s[kb][qq][1]), fmaxf(s[kb][qq][2], s[kb][qq][3])));
;                 mx = xr32_max(xr16_max(mx));
;                 const float mn = fmaxf(mrun[qq], mx), alpha = __builtin_amdgcn_exp2f(mrun[qq] - mn); mrun[qq] = mn;
;                 float ps = 0.f; float p[16];
; #pragma unroll
;                 for (int kb = 0; kb < 4; ++kb)
; #pragma unroll
;                     for (int r = 0; r < 4; ++r) { p[kb * 4 + r] = __builtin_amdgcn_exp2f(s[kb][qq][r] - mn); ps += p[kb * 4 + r]; }
;                 ps = xr32_sum(xr16_sum(ps));
;                 lrun[qq] = lrun[qq] * alpha + ps;
; if (__builtin_amdgcn_ballot_w64(alpha != 1.0f) != 0ull) {
; #pragma unroll
;                     for (int db = 0; db < 8; ++db) o[db][qq] = o[db][qq] * alpha; }
.Latt_gB:
	s_cmp_eq_u32 s46, 0
	s_cbranch_scc1 .Latt_B_dma
	v_add3_u32 v18, s46, v181, -1
	v_cmp_le_i32_e32 vcc, v18, v180
	s_cbranch_vccz .Latt_B_dma
	v_max3_f32 v198, v218, v219, v220
	v_max3_f32 v210, v150, v151, v152
	v_max3_f32 v199, v221, v214, v215
	v_max3_f32 v211, v153, v146, v147
	v_max3_f32 v200, v216, v217, v222
	v_max3_f32 v212, v148, v149, v142
	v_max3_f32 v201, v223, v224, v225
	v_max3_f32 v213, v143, v144, v145
	v_max3_f32 v192, v154, v155, v156
	v_max3_f32 v193, v138, v139, v140
	v_max3_f32 v198, v198, v199, v157
	v_max3_f32 v210, v210, v211, v141
	v_max3_f32 v200, v200, v201, v192
	v_max3_f32 v212, v212, v213, v193
	v_max3_f32 v18, v198, v200, s1
	v_max3_f32 v20, v210, v212, s1
	v_mov_b32_e32 v198, v18
	v_mov_b32_e32 v210, v20
	s_nop 0
	v_permlane16_swap_b32 v18, v198
	v_permlane16_swap_b32 v20, v210
	s_nop 0
	v_max_f32_e32 v18, v18, v198
	v_max_f32_e32 v20, v20, v210
	v_mov_b32_e32 v198, v18
	v_mov_b32_e32 v210, v20
	s_nop 0
	v_permlane32_swap_b32 v18, v198
	v_permlane32_swap_b32 v20, v210
	s_nop 0
	v_max_f32_e32 v18, v18, v198
	v_max_f32_e32 v20, v20, v210
	v_add_f32_e32 v198, 0x41000000, v164
	v_add_f32_e32 v210, 0x41000000, v162
	v_cmp_gt_f32_e32 vcc, v18, v198
	v_cndmask_b32_e32 v21, v164, v18, vcc
	v_cmp_gt_f32_e32 vcc, v20, v210
	v_cndmask_b32_e32 v191, v162, v20, vcc
	v_sub_f32_e32 v18, v164, v21
	v_sub_f32_e32 v20, v162, v191
	v_exp_f32_e32 v18, v18
	v_exp_f32_e32 v20, v20
	v_sub_f32_e32 v218, v218, v21
	v_sub_f32_e32 v219, v219, v21
	v_sub_f32_e32 v220, v220, v21
	v_sub_f32_e32 v221, v221, v21
	v_sub_f32_e32 v214, v214, v21
	v_sub_f32_e32 v215, v215, v21
	v_sub_f32_e32 v216, v216, v21
	v_sub_f32_e32 v217, v217, v21
	v_sub_f32_e32 v222, v222, v21
	v_sub_f32_e32 v223, v223, v21
	v_sub_f32_e32 v224, v224, v21
	v_sub_f32_e32 v225, v225, v21
	v_sub_f32_e32 v154, v154, v21
	v_sub_f32_e32 v155, v155, v21
	v_sub_f32_e32 v156, v156, v21
	v_sub_f32_e32 v157, v157, v21
	v_sub_f32_e32 v150, v150, v191
	v_sub_f32_e32 v151, v151, v191
	v_sub_f32_e32 v152, v152, v191
	v_sub_f32_e32 v153, v153, v191
	v_sub_f32_e32 v146, v146, v191
	v_sub_f32_e32 v147, v147, v191
	v_sub_f32_e32 v148, v148, v191
	v_sub_f32_e32 v149, v149, v191
	v_sub_f32_e32 v142, v142, v191
	v_sub_f32_e32 v143, v143, v191
	v_sub_f32_e32 v144, v144, v191
	v_sub_f32_e32 v145, v145, v191
	v_sub_f32_e32 v138, v138, v191
	v_sub_f32_e32 v139, v139, v191
	v_sub_f32_e32 v140, v140, v191
	v_sub_f32_e32 v141, v141, v191
	v_cmp_neq_f32_e32 vcc, 1.0, v18
	s_cbranch_vccz .Latt_r0_B
	v_pk_mul_f32 v[136:137], v[136:137], v[18:19] op_sel_hi:[1,0]
	v_pk_mul_f32 v[134:135], v[134:135], v[18:19] op_sel_hi:[1,0]
	v_pk_mul_f32 v[108:109], v[108:109], v[18:19] op_sel_hi:[1,0]
	v_pk_mul_f32 v[106:107], v[106:107], v[18:19] op_sel_hi:[1,0]
	v_pk_mul_f32 v[100:101], v[100:101], v[18:19] op_sel_hi:[1,0]
	v_pk_mul_f32 v[98:99], v[98:99], v[18:19] op_sel_hi:[1,0]
	v_pk_mul_f32 v[92:93], v[92:93], v[18:19] op_sel_hi:[1,0]
	v_pk_mul_f32 v[90:91], v[90:91], v[18:19] op_sel_hi:[1,0]
	v_pk_mul_f32 v[84:85], v[84:85], v[18:19] op_sel_hi:[1,0]
	v_pk_mul_f32 v[82:83], v[82:83], v[18:19] op_sel_hi:[1,0]
	v_pk_mul_f32 v[72:73], v[72:73], v[18:19] op_sel_hi:[1,0]
	v_pk_mul_f32 v[70:71], v[70:71], v[18:19] op_sel_hi:[1,0]
	v_pk_mul_f32 v[68:69], v[68:69], v[18:19] op_sel_hi:[1,0]
	v_pk_mul_f32 v[66:67], v[66:67], v[18:19] op_sel_hi:[1,0]
	v_pk_mul_f32 v[56:57], v[56:57], v[18:19] op_sel_hi:[1,0]
	v_pk_mul_f32 v[54:55], v[54:55], v[18:19] op_sel_hi:[1,0]
